# norm loop prefetch + mod GEMV rewrite + P4/P8 bias-table prologue batched
# speedup vs baseline: 1.0086x; 1.0086x over previous
; #define LAS __attribute__((address_space(3)))
; __device__ __forceinline__ float silu_f(float a) { return a / (1.f + __expf(-a)); }
; __global__ void __launch_bounds__(512, 2) hybrid_fwd(Args args) {
;     ...
;         LAS float* red = (LAS float*)(lds + 12288);
;         for (int cb = blk; cb < 256; cb += G) {
;             const int c4 = lane & 15, ks = lane >> 4;
;             f32x4 a0 = {0.f, 0.f, 0.f, 0.f}, a1 = {0.f, 0.f, 0.f, 0.f};
;             if (c4 < 9) {
;                 const int j = 36 * cb + 4 * c4, kbase = wave * 128 + ks * 32;
; #pragma unroll 8
;                 for (int i = 0; i < 32; ++i) { const int k = kbase + i; const f32x4 wv = *(const f32x4*)(w_ada + (size_t)k * NADA + j);
;                     a0 += wv * silu_f(cvec[k]); a1 += wv * silu_f(cvec[DM + k]); }
.LBB0_51:
	s_cmpk_gt_i32 s2, 0xff
	s_cbranch_scc1 .LBB0_61
	v_mbcnt_lo_u32_b32 v5, -1, 0
	v_mbcnt_hi_u32_b32 v5, -1, v5
	v_and_b32_e32 v8, 64, v5
	v_xor_b32_e32 v7, 16, v5
	v_add_u32_e32 v8, 64, v8
	v_cmp_lt_i32_e32 vcc, v7, v8
	v_lshlrev_b32_e32 v4, 1, v160
	v_and_b32_e32 v4, 0xffffffe0, v4
	v_cndmask_b32_e32 v7, v5, v7, vcc
	v_lshlrev_b32_e32 v49, 2, v7
	v_xor_b32_e32 v7, 32, v5
	v_cmp_lt_i32_e32 vcc, v7, v8
	s_mov_b32 s0, s91
	v_mov_b32_e32 v9, 0x1b0
	v_cndmask_b32_e32 v5, v5, v7, vcc
	v_lshlrev_b32_e32 v66, 2, v5
	v_subrev_co_u32_e32 v5, vcc, 36, v226
	v_lshl_add_u32 v4, s0, 7, v4
	s_nop 0
	v_cndmask_b32_e32 v48, v5, v226, vcc
	v_mov_b32_e32 v5, 0x2400
	v_cmp_lt_u32_e32 vcc, 35, v226
	s_mul_i32 s0, s91, 0x120
	v_mov_b32_e32 v10, 0x2d0
	v_cndmask_b32_e32 v68, 0, v5, vcc
	v_mov_b32_e32 v5, 0x90
	v_cndmask_b32_e32 v8, 0, v5, vcc
	v_mov_b32_e32 v5, 0x120
	v_cndmask_b32_e32 v9, v5, v9, vcc
	v_mov_b32_e32 v5, 0x240
	s_add_i32 s0, s0, 0
	v_cndmask_b32_e32 v10, v5, v10, vcc
	v_mov_b32_e32 v5, 0x360
	v_mov_b32_e32 v11, 0x3f0
	v_lshl_add_u32 v67, v160, 4, s0
	s_movk_i32 s0, 0x48
	v_cndmask_b32_e32 v11, v5, v11, vcc
	v_mov_b32_e32 v5, 0x480
	v_mov_b32_e32 v12, 0x510
	s_waitcnt lgkmcnt(0)
	v_mov_b32_e32 v2, s64
	v_mov_b32_e32 v3, s65
	v_cmp_gt_u32_e64 s[8:9], s0, v226
	v_cndmask_b32_e32 v12, v5, v12, vcc
	v_mov_b32_e32 v5, 0x5a0
	v_mov_b32_e32 v13, 0x630
	s_mov_b32 s0, 0x9000
	v_cndmask_b32_e32 v13, v5, v13, vcc
	v_mov_b32_e32 v5, 0x6c0
	v_mov_b32_e32 v14, 0x750
	v_mad_i64_i32 v[2:3], s[0:1], v4, s0, v[2:3]
	v_cndmask_b32_e32 v14, v5, v14, vcc
	v_mov_b32_e32 v5, 0x7e0
	v_mov_b32_e32 v15, 0x870
	s_mov_b64 s[0:1], 0x3f000
	v_mov_b32_e32 v0, s62
	v_mov_b32_e32 v1, s63
	v_and_b32_e32 v6, 15, v160
	v_lshl_add_u32 v7, v48, 2, 0
	v_cndmask_b32_e32 v15, v5, v15, vcc
	v_ashrrev_i32_e32 v5, 31, v4
	v_lshl_add_u64 v[50:51], v[2:3], 0, s[0:1]
	s_mul_i32 s0, s2, 36
	v_cmp_gt_u32_e64 s[4:5], 9, v6
	v_cmp_gt_i32_e64 s[6:7], 9, v160
	v_lshl_add_u32 v52, v6, 2, s0
	v_lshl_add_u64 v[54:55], v[4:5], 2, v[0:1]
	s_mov_b32 s3, 0xfffee000
	s_mov_b32 s58, 0xffff7000
	s_mov_b64 s[52:53], 0x48000
	v_add_u32_e32 v69, v7, v8
	v_add_u32_e32 v70, v7, v9
	v_add_u32_e32 v71, v7, v10
	v_add_u32_e32 v72, v7, v11
	v_add_u32_e32 v73, v7, v12
	v_add_u32_e32 v74, v7, v13
	v_add_u32_e32 v75, v7, v14
	v_add_u32_e32 v76, v7, v15
	s_and_b32 s59, s2, 7
	s_lshl_b32 s59, s59, 5
	s_lshr_b32 s0, s2, 3
	s_or_b32 s59, s59, s0
	s_branch .LBB0_54

; __device__ __forceinline__ float silu_f(float a) { return a / (1.f + __expf(-a)); }
; __global__ void __launch_bounds__(512, 2) hybrid_fwd(Args args) {
;     ...
;                 const int j = 36 * cb + 4 * c4, kbase = wave * 128 + ks * 32;
; #pragma unroll 8
;                 for (int i = 0; i < 32; ++i) { const int k = kbase + i; const f32x4 wv = *(const f32x4*)(w_ada + (size_t)k * NADA + j);
;                     a0 += wv * silu_f(cvec[k]); a1 += wv * silu_f(cvec[DM + k]); }
.LBB0_54:
	v_lshlrev_b32_e32 v0, 2, v226
	v_add_u32_e32 v1, 0x1000, v0
	global_load_dword v2, v0, s[62:63]
	global_load_dword v3, v0, s[62:63] offset:2048
	global_load_dword v4, v1, s[62:63]
	global_load_dword v5, v1, s[62:63] offset:2048
	s_mul_i32 s0, s91, 0x480000
	s_mul_i32 s1, s59, 0x90
	s_add_u32 s0, s0, s1
	s_add_u32 s0, s64, s0
	s_addc_u32 s1, s65, 0
	v_lshrrev_b32_e32 v6, 4, v160
	v_and_b32_e32 v7, 15, v160
	v_mul_u32_u24_e32 v6, 0x120000, v6
	v_lshl_add_u32 v6, v7, 4, v6
	v_mov_b32_e32 v58, 0
	v_mov_b32_e32 v59, 0
	v_mov_b32_e32 v60, 0
	v_mov_b32_e32 v61, 0
	v_mov_b32_e32 v62, 0
	v_mov_b32_e32 v63, 0
	v_mov_b32_e32 v64, 0
	v_mov_b32_e32 v65, 0
	s_and_saveexec_b64 s[54:55], s[4:5]
	s_lshl_b32 s3, s91, 2
	s_mul_i32 s10, s3, 0x9000
	s_add_u32 s0, s0, s10
	s_addc_u32 s1, s1, 0
	global_load_dwordx4 v[80:83], v6, s[0:1]
	s_add_u32 s0, s0, 0x9000
	s_addc_u32 s1, s1, 0
	s_add_i32 s3, s3, 1
	s_cmp_eq_u32 s3, 32
	s_cselect_b32 s10, 0x120000, 0
	s_cselect_b32 s3, 0, s3
	s_sub_u32 s0, s0, s10
	s_subb_u32 s1, s1, 0
	global_load_dwordx4 v[84:87], v6, s[0:1]
	s_add_u32 s0, s0, 0x9000
	s_addc_u32 s1, s1, 0
	s_add_i32 s3, s3, 1
	s_cmp_eq_u32 s3, 32
	s_cselect_b32 s10, 0x120000, 0
	s_cselect_b32 s3, 0, s3
	s_sub_u32 s0, s0, s10
	s_subb_u32 s1, s1, 0
	global_load_dwordx4 v[88:91], v6, s[0:1]
	s_add_u32 s0, s0, 0x9000
	s_addc_u32 s1, s1, 0
	s_add_i32 s3, s3, 1
	s_cmp_eq_u32 s3, 32
	s_cselect_b32 s10, 0x120000, 0
	s_cselect_b32 s3, 0, s3
	s_sub_u32 s0, s0, s10
	s_subb_u32 s1, s1, 0
	global_load_dwordx4 v[92:95], v6, s[0:1]
	s_add_u32 s0, s0, 0x9000
	s_addc_u32 s1, s1, 0
	s_add_i32 s3, s3, 1
	s_cmp_eq_u32 s3, 32
	s_cselect_b32 s10, 0x120000, 0
	s_cselect_b32 s3, 0, s3
	s_sub_u32 s0, s0, s10
	s_subb_u32 s1, s1, 0
	global_load_dwordx4 v[96:99], v6, s[0:1]
	s_add_u32 s0, s0, 0x9000
	s_addc_u32 s1, s1, 0
	s_add_i32 s3, s3, 1
	s_cmp_eq_u32 s3, 32
	s_cselect_b32 s10, 0x120000, 0
	s_cselect_b32 s3, 0, s3
	s_sub_u32 s0, s0, s10
	s_subb_u32 s1, s1, 0
	global_load_dwordx4 v[100:103], v6, s[0:1]
	s_add_u32 s0, s0, 0x9000
	s_addc_u32 s1, s1, 0
	s_add_i32 s3, s3, 1
	s_cmp_eq_u32 s3, 32
	s_cselect_b32 s10, 0x120000, 0
	s_cselect_b32 s3, 0, s3
	s_sub_u32 s0, s0, s10
	s_subb_u32 s1, s1, 0
	global_load_dwordx4 v[104:107], v6, s[0:1]
	s_add_u32 s0, s0, 0x9000
	s_addc_u32 s1, s1, 0
	s_add_i32 s3, s3, 1
	s_cmp_eq_u32 s3, 32
	s_cselect_b32 s10, 0x120000, 0
	s_cselect_b32 s3, 0, s3
	s_sub_u32 s0, s0, s10
	s_subb_u32 s1, s1, 0
	global_load_dwordx4 v[108:111], v6, s[0:1]
	s_add_u32 s0, s0, 0x9000
	s_addc_u32 s1, s1, 0
	s_add_i32 s3, s3, 1
	s_cmp_eq_u32 s3, 32
	s_cselect_b32 s10, 0x120000, 0
	s_cselect_b32 s3, 0, s3
	s_sub_u32 s0, s0, s10
	s_subb_u32 s1, s1, 0
	global_load_dwordx4 v[112:115], v6, s[0:1]
	s_add_u32 s0, s0, 0x9000
	s_addc_u32 s1, s1, 0
	s_add_i32 s3, s3, 1
	s_cmp_eq_u32 s3, 32
	s_cselect_b32 s10, 0x120000, 0
	s_cselect_b32 s3, 0, s3
	s_sub_u32 s0, s0, s10
	s_subb_u32 s1, s1, 0
	global_load_dwordx4 v[116:119], v6, s[0:1]
	s_add_u32 s0, s0, 0x9000
	s_addc_u32 s1, s1, 0
	s_add_i32 s3, s3, 1
	s_cmp_eq_u32 s3, 32
	s_cselect_b32 s10, 0x120000, 0
	s_cselect_b32 s3, 0, s3
	s_sub_u32 s0, s0, s10
	s_subb_u32 s1, s1, 0
	global_load_dwordx4 v[120:123], v6, s[0:1]
	s_add_u32 s0, s0, 0x9000
	s_addc_u32 s1, s1, 0
	s_add_i32 s3, s3, 1
	s_cmp_eq_u32 s3, 32
	s_cselect_b32 s10, 0x120000, 0
	s_cselect_b32 s3, 0, s3
	s_sub_u32 s0, s0, s10
	s_subb_u32 s1, s1, 0
	global_load_dwordx4 v[124:127], v6, s[0:1]
	s_add_u32 s0, s0, 0x9000
	s_addc_u32 s1, s1, 0
	s_add_i32 s3, s3, 1
	s_cmp_eq_u32 s3, 32
	s_cselect_b32 s10, 0x120000, 0
	s_cselect_b32 s3, 0, s3
	s_sub_u32 s0, s0, s10
	s_subb_u32 s1, s1, 0
	global_load_dwordx4 v[128:131], v6, s[0:1]
	s_add_u32 s0, s0, 0x9000
	s_addc_u32 s1, s1, 0
	s_add_i32 s3, s3, 1
	s_cmp_eq_u32 s3, 32
	s_cselect_b32 s10, 0x120000, 0
	s_cselect_b32 s3, 0, s3
	s_sub_u32 s0, s0, s10
	s_subb_u32 s1, s1, 0
	global_load_dwordx4 v[132:135], v6, s[0:1]
	s_add_u32 s0, s0, 0x9000
	s_addc_u32 s1, s1, 0
	s_add_i32 s3, s3, 1
	s_cmp_eq_u32 s3, 32
	s_cselect_b32 s10, 0x120000, 0
	s_cselect_b32 s3, 0, s3
	s_sub_u32 s0, s0, s10
	s_subb_u32 s1, s1, 0
	global_load_dwordx4 v[136:139], v6, s[0:1]
	s_add_u32 s0, s0, 0x9000
	s_addc_u32 s1, s1, 0
	s_add_i32 s3, s3, 1
	s_cmp_eq_u32 s3, 32
	s_cselect_b32 s10, 0x120000, 0
	s_cselect_b32 s3, 0, s3
	s_sub_u32 s0, s0, s10
	s_subb_u32 s1, s1, 0
	global_load_dwordx4 v[140:143], v6, s[0:1]
	s_add_u32 s0, s0, 0x9000
	s_addc_u32 s1, s1, 0
	s_add_i32 s3, s3, 1
	s_cmp_eq_u32 s3, 32
	s_cselect_b32 s10, 0x120000, 0
	s_cselect_b32 s3, 0, s3
	s_sub_u32 s0, s0, s10
	s_subb_u32 s1, s1, 0
	global_load_dwordx4 v[144:147], v6, s[0:1]
	s_add_u32 s0, s0, 0x9000
	s_addc_u32 s1, s1, 0
	s_add_i32 s3, s3, 1
	s_cmp_eq_u32 s3, 32
	s_cselect_b32 s10, 0x120000, 0
	s_cselect_b32 s3, 0, s3
	s_sub_u32 s0, s0, s10
	s_subb_u32 s1, s1, 0
	global_load_dwordx4 v[148:151], v6, s[0:1]
	s_add_u32 s0, s0, 0x9000
	s_addc_u32 s1, s1, 0
	s_add_i32 s3, s3, 1
	s_cmp_eq_u32 s3, 32
	s_cselect_b32 s10, 0x120000, 0
	s_cselect_b32 s3, 0, s3
	s_sub_u32 s0, s0, s10
	s_subb_u32 s1, s1, 0
	global_load_dwordx4 v[152:155], v6, s[0:1]
	s_add_u32 s0, s0, 0x9000
	s_addc_u32 s1, s1, 0
	s_add_i32 s3, s3, 1
	s_cmp_eq_u32 s3, 32
	s_cselect_b32 s10, 0x120000, 0
	s_cselect_b32 s3, 0, s3
	s_sub_u32 s0, s0, s10
	s_subb_u32 s1, s1, 0
	global_load_dwordx4 v[156:159], v6, s[0:1]
	s_add_u32 s0, s0, 0x9000
	s_addc_u32 s1, s1, 0
	s_add_i32 s3, s3, 1
	s_cmp_eq_u32 s3, 32
	s_cselect_b32 s10, 0x120000, 0
	s_cselect_b32 s3, 0, s3
	s_sub_u32 s0, s0, s10
	s_subb_u32 s1, s1, 0
	global_load_dwordx4 v[164:167], v6, s[0:1]
	s_add_u32 s0, s0, 0x9000
	s_addc_u32 s1, s1, 0
	s_add_i32 s3, s3, 1
	s_cmp_eq_u32 s3, 32
; __device__ __forceinline__ float silu_f(float a) { return a / (1.f + __expf(-a)); }
; __global__ void __launch_bounds__(512, 2) hybrid_fwd(Args args) {
;     ...
;                 for (int i = 0; i < 32; ++i) { const int k = kbase + i; const f32x4 wv = *(const f32x4*)(w_ada + (size_t)k * NADA + j);
;                     a0 += wv * silu_f(cvec[k]); a1 += wv * silu_f(cvec[DM + k]); }
	s_cselect_b32 s10, 0x120000, 0
	s_cselect_b32 s3, 0, s3
	s_sub_u32 s0, s0, s10
	s_subb_u32 s1, s1, 0
	global_load_dwordx4 v[168:171], v6, s[0:1]
	s_add_u32 s0, s0, 0x9000
	s_addc_u32 s1, s1, 0
	s_add_i32 s3, s3, 1
	s_cmp_eq_u32 s3, 32
	s_cselect_b32 s10, 0x120000, 0
	s_cselect_b32 s3, 0, s3
	s_sub_u32 s0, s0, s10
	s_subb_u32 s1, s1, 0
	global_load_dwordx4 v[172:175], v6, s[0:1]
	s_add_u32 s0, s0, 0x9000
	s_addc_u32 s1, s1, 0
	s_add_i32 s3, s3, 1
	s_cmp_eq_u32 s3, 32
	s_cselect_b32 s10, 0x120000, 0
	s_cselect_b32 s3, 0, s3
	s_sub_u32 s0, s0, s10
	s_subb_u32 s1, s1, 0
	global_load_dwordx4 v[176:179], v6, s[0:1]
	s_add_u32 s0, s0, 0x9000
	s_addc_u32 s1, s1, 0
	s_add_i32 s3, s3, 1
	s_cmp_eq_u32 s3, 32
	s_cselect_b32 s10, 0x120000, 0
	s_cselect_b32 s3, 0, s3
	s_sub_u32 s0, s0, s10
	s_subb_u32 s1, s1, 0
	global_load_dwordx4 v[180:183], v6, s[0:1]
	s_add_u32 s0, s0, 0x9000
	s_addc_u32 s1, s1, 0
	s_add_i32 s3, s3, 1
	s_cmp_eq_u32 s3, 32
	s_cselect_b32 s10, 0x120000, 0
	s_cselect_b32 s3, 0, s3
	s_sub_u32 s0, s0, s10
	s_subb_u32 s1, s1, 0
	global_load_dwordx4 v[184:187], v6, s[0:1]
	s_add_u32 s0, s0, 0x9000
	s_addc_u32 s1, s1, 0
	s_add_i32 s3, s3, 1
	s_cmp_eq_u32 s3, 32
	s_cselect_b32 s10, 0x120000, 0
	s_cselect_b32 s3, 0, s3
	s_sub_u32 s0, s0, s10
	s_subb_u32 s1, s1, 0
	global_load_dwordx4 v[188:191], v6, s[0:1]
	s_add_u32 s0, s0, 0x9000
	s_addc_u32 s1, s1, 0
	s_add_i32 s3, s3, 1
	s_cmp_eq_u32 s3, 32
	s_cselect_b32 s10, 0x120000, 0
	s_cselect_b32 s3, 0, s3
	s_sub_u32 s0, s0, s10
	s_subb_u32 s1, s1, 0
	global_load_dwordx4 v[192:195], v6, s[0:1]
	s_add_u32 s0, s0, 0x9000
	s_addc_u32 s1, s1, 0
	s_add_i32 s3, s3, 1
	s_cmp_eq_u32 s3, 32
	s_cselect_b32 s10, 0x120000, 0
	s_cselect_b32 s3, 0, s3
	s_sub_u32 s0, s0, s10
	s_subb_u32 s1, s1, 0
	global_load_dwordx4 v[196:199], v6, s[0:1]
	s_add_u32 s0, s0, 0x9000
	s_addc_u32 s1, s1, 0
	s_add_i32 s3, s3, 1
	s_cmp_eq_u32 s3, 32
	s_cselect_b32 s10, 0x120000, 0
	s_cselect_b32 s3, 0, s3
	s_sub_u32 s0, s0, s10
	s_subb_u32 s1, s1, 0
	global_load_dwordx4 v[200:203], v6, s[0:1]
	s_add_u32 s0, s0, 0x9000
	s_addc_u32 s1, s1, 0
	s_add_i32 s3, s3, 1
	s_cmp_eq_u32 s3, 32
	s_cselect_b32 s10, 0x120000, 0
	s_cselect_b32 s3, 0, s3
	s_sub_u32 s0, s0, s10
	s_subb_u32 s1, s1, 0
	global_load_dwordx4 v[204:207], v6, s[0:1]
	s_add_u32 s0, s0, 0x9000
	s_addc_u32 s1, s1, 0
	s_add_i32 s3, s3, 1
	s_cmp_eq_u32 s3, 32
	s_cselect_b32 s10, 0x120000, 0
	s_cselect_b32 s3, 0, s3
	s_sub_u32 s0, s0, s10
	s_subb_u32 s1, s1, 0
	global_load_dwordx4 v[208:211], v6, s[0:1]
	s_or_b64 exec, exec, s[54:55]
	s_waitcnt vmcnt(32)
	v_mul_f32_e32 v8, 0xbfb8aa3b, v2
	v_mul_f32_e32 v16, 0xbfb8aa3b, v3
	v_mul_f32_e32 v24, 0xbfb8aa3b, v4
	v_mul_f32_e32 v32, 0xbfb8aa3b, v5
	v_exp_f32_e32 v8, v8
	v_exp_f32_e32 v16, v16
	v_exp_f32_e32 v24, v24
	v_exp_f32_e32 v32, v32
	s_nop 0
	v_add_f32_e32 v9, 1.0, v8
	v_add_f32_e32 v17, 1.0, v16
	v_add_f32_e32 v25, 1.0, v24
	v_add_f32_e32 v33, 1.0, v32
	v_div_scale_f32 v10, s[10:11], v9, v9, v2
	v_div_scale_f32 v18, s[10:11], v17, v17, v3
	v_div_scale_f32 v26, s[10:11], v25, v25, v4
	v_div_scale_f32 v34, s[10:11], v33, v33, v5
	v_rcp_f32_e32 v11, v10
	v_rcp_f32_e32 v19, v18
	v_rcp_f32_e32 v27, v26
	v_rcp_f32_e32 v35, v34
	s_nop 0
	v_fma_f32 v12, -v10, v11, 1.0
	v_fma_f32 v20, -v18, v19, 1.0
	v_fma_f32 v28, -v26, v27, 1.0
	v_fma_f32 v36, -v34, v35, 1.0
	v_fmac_f32_e32 v11, v12, v11
	v_fmac_f32_e32 v19, v20, v19
	v_fmac_f32_e32 v27, v28, v27
	v_fmac_f32_e32 v35, v36, v35
	v_div_scale_f32 v13, vcc, v2, v9, v2
	v_mul_f32_e32 v14, v13, v11
	v_fma_f32 v12, -v10, v14, v13
	v_fmac_f32_e32 v14, v12, v11
	v_fma_f32 v12, -v10, v14, v13
	s_nop 0
	v_div_fmas_f32 v12, v12, v11, v14
	v_div_fixup_f32 v2, v12, v9, v2
	v_div_scale_f32 v21, vcc, v3, v17, v3
	v_mul_f32_e32 v22, v21, v19
	v_fma_f32 v20, -v18, v22, v21
	v_fmac_f32_e32 v22, v20, v19
	v_fma_f32 v20, -v18, v22, v21
	s_nop 0
	v_div_fmas_f32 v20, v20, v19, v22
	v_div_fixup_f32 v3, v20, v17, v3
	v_div_scale_f32 v29, vcc, v4, v25, v4
	v_mul_f32_e32 v30, v29, v27
	v_fma_f32 v28, -v26, v30, v29
	v_fmac_f32_e32 v30, v28, v27
	v_fma_f32 v28, -v26, v30, v29
	s_nop 0
	v_div_fmas_f32 v28, v28, v27, v30
	v_div_fixup_f32 v4, v28, v25, v4
	v_div_scale_f32 v37, vcc, v5, v33, v5
	v_mul_f32_e32 v38, v37, v35
	v_fma_f32 v36, -v34, v38, v37
	v_fmac_f32_e32 v38, v36, v35
	v_fma_f32 v36, -v34, v38, v37
	s_nop 0
	v_div_fmas_f32 v36, v36, v35, v38
	v_div_fixup_f32 v5, v36, v33, v5
	v_add_u32_e32 v0, 0x20800, v0
	ds_write_b32 v0, v2
	ds_write_b32 v0, v3 offset:2048
	ds_write_b32 v0, v4 offset:4096
	ds_write_b32 v0, v5 offset:6144
	s_waitcnt lgkmcnt(0)
	s_barrier
	s_and_saveexec_b64 s[54:55], s[4:5]
	s_cbranch_execz .LBB0_57
; __device__ __forceinline__ float silu_f(float a) { return a / (1.f + __expf(-a)); }
; __global__ void __launch_bounds__(512, 2) hybrid_fwd(Args args) {
;     ...
;                 const int j = 36 * cb + 4 * c4, kbase = wave * 128 + ks * 32;
; #pragma unroll 8
;                 for (int i = 0; i < 32; ++i) { const int k = kbase + i; const f32x4 wv = *(const f32x4*)(w_ada + (size_t)k * NADA + j);
;                     a0 += wv * silu_f(cvec[k]); a1 += wv * silu_f(cvec[DM + k]); }
	v_lshrrev_b32_e32 v7, 4, v160
	s_lshl_b32 s0, s91, 9
	v_lshl_add_u32 v7, v7, 7, s0
	v_add_u32_e32 v7, 0x20800, v7
	s_add_i32 s10, s91, 1
	s_and_b32 s10, s10, 7
	s_lshl_b32 s10, s10, 4
	v_add_u32_e32 v6, s10, v7
	ds_read_b128 v[8:11], v6
	ds_read_b128 v[40:43], v6 offset:4096
	s_add_i32 s10, s91, 2
	s_and_b32 s10, s10, 7
	s_lshl_b32 s10, s10, 4
	v_add_u32_e32 v6, s10, v7
	ds_read_b128 v[12:15], v6
	ds_read_b128 v[44:47], v6 offset:4096
	s_add_i32 s10, s91, 3
	s_and_b32 s10, s10, 7
	s_lshl_b32 s10, s10, 4
	v_add_u32_e32 v6, s10, v7
	ds_read_b128 v[16:19], v6
	ds_read_b128 v[212:215], v6 offset:4096
	s_add_i32 s10, s91, 4
	s_and_b32 s10, s10, 7
	s_lshl_b32 s10, s10, 4
	v_add_u32_e32 v6, s10, v7
	ds_read_b128 v[20:23], v6
	ds_read_b128 v[216:219], v6 offset:4096
	s_add_i32 s10, s91, 5
	s_and_b32 s10, s10, 7
	s_lshl_b32 s10, s10, 4
	v_add_u32_e32 v6, s10, v7
	ds_read_b128 v[24:27], v6
	ds_read_b128 v[220:223], v6 offset:4096
	s_add_i32 s10, s91, 6
	s_and_b32 s10, s10, 7
	s_lshl_b32 s10, s10, 4
	v_add_u32_e32 v6, s10, v7
	ds_read_b128 v[28:31], v6
	ds_read_b128 v[228:231], v6 offset:4096
	s_add_i32 s10, s91, 7
	s_and_b32 s10, s10, 7
	s_lshl_b32 s10, s10, 4
	v_add_u32_e32 v6, s10, v7
	ds_read_b128 v[32:35], v6
	ds_read_b128 v[232:235], v6 offset:4096
	s_add_i32 s10, s91, 0
	s_and_b32 s10, s10, 7
	s_lshl_b32 s10, s10, 4
	v_add_u32_e32 v6, s10, v7
	ds_read_b128 v[0:3], v6
	ds_read_b128 v[36:39], v6 offset:4096
	s_waitcnt lgkmcnt(0)
	s_waitcnt vmcnt(31)
	v_pk_fma_f32 v[62:63], v[80:81], v[0:1], v[62:63] op_sel_hi:[1,0,1]
	v_pk_fma_f32 v[60:61], v[82:83], v[0:1], v[60:61] op_sel_hi:[1,0,1]
	v_pk_fma_f32 v[64:65], v[80:81], v[36:37], v[64:65] op_sel_hi:[1,0,1]
	v_pk_fma_f32 v[58:59], v[82:83], v[36:37], v[58:59] op_sel_hi:[1,0,1]
	s_waitcnt vmcnt(30)
	v_pk_fma_f32 v[62:63], v[84:85], v[0:1], v[62:63] op_sel:[0,1,0] op_sel_hi:[1,1,1]
	v_pk_fma_f32 v[60:61], v[86:87], v[0:1], v[60:61] op_sel:[0,1,0] op_sel_hi:[1,1,1]
	v_pk_fma_f32 v[64:65], v[84:85], v[36:37], v[64:65] op_sel:[0,1,0] op_sel_hi:[1,1,1]
	v_pk_fma_f32 v[58:59], v[86:87], v[36:37], v[58:59] op_sel:[0,1,0] op_sel_hi:[1,1,1]
	s_waitcnt vmcnt(29)
	v_pk_fma_f32 v[62:63], v[88:89], v[2:3], v[62:63] op_sel_hi:[1,0,1]
	v_pk_fma_f32 v[60:61], v[90:91], v[2:3], v[60:61] op_sel_hi:[1,0,1]
	v_pk_fma_f32 v[64:65], v[88:89], v[38:39], v[64:65] op_sel_hi:[1,0,1]
	v_pk_fma_f32 v[58:59], v[90:91], v[38:39], v[58:59] op_sel_hi:[1,0,1]
	s_waitcnt vmcnt(28)
	v_pk_fma_f32 v[62:63], v[92:93], v[2:3], v[62:63] op_sel:[0,1,0] op_sel_hi:[1,1,1]
	v_pk_fma_f32 v[60:61], v[94:95], v[2:3], v[60:61] op_sel:[0,1,0] op_sel_hi:[1,1,1]
	v_pk_fma_f32 v[64:65], v[92:93], v[38:39], v[64:65] op_sel:[0,1,0] op_sel_hi:[1,1,1]
	v_pk_fma_f32 v[58:59], v[94:95], v[38:39], v[58:59] op_sel:[0,1,0] op_sel_hi:[1,1,1]
	s_waitcnt vmcnt(27)
	v_pk_fma_f32 v[62:63], v[96:97], v[8:9], v[62:63] op_sel_hi:[1,0,1]
	v_pk_fma_f32 v[60:61], v[98:99], v[8:9], v[60:61] op_sel_hi:[1,0,1]
	v_pk_fma_f32 v[64:65], v[96:97], v[40:41], v[64:65] op_sel_hi:[1,0,1]
	v_pk_fma_f32 v[58:59], v[98:99], v[40:41], v[58:59] op_sel_hi:[1,0,1]
	s_waitcnt vmcnt(26)
	v_pk_fma_f32 v[62:63], v[100:101], v[8:9], v[62:63] op_sel:[0,1,0] op_sel_hi:[1,1,1]
	v_pk_fma_f32 v[60:61], v[102:103], v[8:9], v[60:61] op_sel:[0,1,0] op_sel_hi:[1,1,1]
	v_pk_fma_f32 v[64:65], v[100:101], v[40:41], v[64:65] op_sel:[0,1,0] op_sel_hi:[1,1,1]
	v_pk_fma_f32 v[58:59], v[102:103], v[40:41], v[58:59] op_sel:[0,1,0] op_sel_hi:[1,1,1]
	s_waitcnt vmcnt(25)
	v_pk_fma_f32 v[62:63], v[104:105], v[10:11], v[62:63] op_sel_hi:[1,0,1]
	v_pk_fma_f32 v[60:61], v[106:107], v[10:11], v[60:61] op_sel_hi:[1,0,1]
	v_pk_fma_f32 v[64:65], v[104:105], v[42:43], v[64:65] op_sel_hi:[1,0,1]
	v_pk_fma_f32 v[58:59], v[106:107], v[42:43], v[58:59] op_sel_hi:[1,0,1]
	s_waitcnt vmcnt(24)
	v_pk_fma_f32 v[62:63], v[108:109], v[10:11], v[62:63] op_sel:[0,1,0] op_sel_hi:[1,1,1]
	v_pk_fma_f32 v[60:61], v[110:111], v[10:11], v[60:61] op_sel:[0,1,0] op_sel_hi:[1,1,1]
	v_pk_fma_f32 v[64:65], v[108:109], v[42:43], v[64:65] op_sel:[0,1,0] op_sel_hi:[1,1,1]
	v_pk_fma_f32 v[58:59], v[110:111], v[42:43], v[58:59] op_sel:[0,1,0] op_sel_hi:[1,1,1]
	s_waitcnt vmcnt(23)
	v_pk_fma_f32 v[62:63], v[112:113], v[12:13], v[62:63] op_sel_hi:[1,0,1]
	v_pk_fma_f32 v[60:61], v[114:115], v[12:13], v[60:61] op_sel_hi:[1,0,1]
	v_pk_fma_f32 v[64:65], v[112:113], v[44:45], v[64:65] op_sel_hi:[1,0,1]
	v_pk_fma_f32 v[58:59], v[114:115], v[44:45], v[58:59] op_sel_hi:[1,0,1]
	s_waitcnt vmcnt(22)
	v_pk_fma_f32 v[62:63], v[116:117], v[12:13], v[62:63] op_sel:[0,1,0] op_sel_hi:[1,1,1]
	v_pk_fma_f32 v[60:61], v[118:119], v[12:13], v[60:61] op_sel:[0,1,0] op_sel_hi:[1,1,1]
	v_pk_fma_f32 v[64:65], v[116:117], v[44:45], v[64:65] op_sel:[0,1,0] op_sel_hi:[1,1,1]
	v_pk_fma_f32 v[58:59], v[118:119], v[44:45], v[58:59] op_sel:[0,1,0] op_sel_hi:[1,1,1]
	s_waitcnt vmcnt(21)
	v_pk_fma_f32 v[62:63], v[120:121], v[14:15], v[62:63] op_sel_hi:[1,0,1]
	v_pk_fma_f32 v[60:61], v[122:123], v[14:15], v[60:61] op_sel_hi:[1,0,1]
	v_pk_fma_f32 v[64:65], v[120:121], v[46:47], v[64:65] op_sel_hi:[1,0,1]
	v_pk_fma_f32 v[58:59], v[122:123], v[46:47], v[58:59] op_sel_hi:[1,0,1]
	s_waitcnt vmcnt(20)
	v_pk_fma_f32 v[62:63], v[124:125], v[14:15], v[62:63] op_sel:[0,1,0] op_sel_hi:[1,1,1]
	v_pk_fma_f32 v[60:61], v[126:127], v[14:15], v[60:61] op_sel:[0,1,0] op_sel_hi:[1,1,1]
	v_pk_fma_f32 v[64:65], v[124:125], v[46:47], v[64:65] op_sel:[0,1,0] op_sel_hi:[1,1,1]
	v_pk_fma_f32 v[58:59], v[126:127], v[46:47], v[58:59] op_sel:[0,1,0] op_sel_hi:[1,1,1]
	s_waitcnt vmcnt(19)
; __device__ __forceinline__ float silu_f(float a) { return a / (1.f + __expf(-a)); }
; __global__ void __launch_bounds__(512, 2) hybrid_fwd(Args args) {
;     ...
; #pragma unroll 8
;                 for (int i = 0; i < 32; ++i) { const int k = kbase + i; const f32x4 wv = *(const f32x4*)(w_ada + (size_t)k * NADA + j);
;                     a0 += wv * silu_f(cvec[k]); a1 += wv * silu_f(cvec[DM + k]); }
	v_pk_fma_f32 v[62:63], v[128:129], v[16:17], v[62:63] op_sel_hi:[1,0,1]
	v_pk_fma_f32 v[60:61], v[130:131], v[16:17], v[60:61] op_sel_hi:[1,0,1]
	v_pk_fma_f32 v[64:65], v[128:129], v[212:213], v[64:65] op_sel_hi:[1,0,1]
	v_pk_fma_f32 v[58:59], v[130:131], v[212:213], v[58:59] op_sel_hi:[1,0,1]
	s_waitcnt vmcnt(18)
	v_pk_fma_f32 v[62:63], v[132:133], v[16:17], v[62:63] op_sel:[0,1,0] op_sel_hi:[1,1,1]
	v_pk_fma_f32 v[60:61], v[134:135], v[16:17], v[60:61] op_sel:[0,1,0] op_sel_hi:[1,1,1]
	v_pk_fma_f32 v[64:65], v[132:133], v[212:213], v[64:65] op_sel:[0,1,0] op_sel_hi:[1,1,1]
	v_pk_fma_f32 v[58:59], v[134:135], v[212:213], v[58:59] op_sel:[0,1,0] op_sel_hi:[1,1,1]
	s_waitcnt vmcnt(17)
	v_pk_fma_f32 v[62:63], v[136:137], v[18:19], v[62:63] op_sel_hi:[1,0,1]
	v_pk_fma_f32 v[60:61], v[138:139], v[18:19], v[60:61] op_sel_hi:[1,0,1]
	v_pk_fma_f32 v[64:65], v[136:137], v[214:215], v[64:65] op_sel_hi:[1,0,1]
	v_pk_fma_f32 v[58:59], v[138:139], v[214:215], v[58:59] op_sel_hi:[1,0,1]
	s_waitcnt vmcnt(16)
	v_pk_fma_f32 v[62:63], v[140:141], v[18:19], v[62:63] op_sel:[0,1,0] op_sel_hi:[1,1,1]
	v_pk_fma_f32 v[60:61], v[142:143], v[18:19], v[60:61] op_sel:[0,1,0] op_sel_hi:[1,1,1]
	v_pk_fma_f32 v[64:65], v[140:141], v[214:215], v[64:65] op_sel:[0,1,0] op_sel_hi:[1,1,1]
	v_pk_fma_f32 v[58:59], v[142:143], v[214:215], v[58:59] op_sel:[0,1,0] op_sel_hi:[1,1,1]
	s_waitcnt vmcnt(15)
	v_pk_fma_f32 v[62:63], v[144:145], v[20:21], v[62:63] op_sel_hi:[1,0,1]
	v_pk_fma_f32 v[60:61], v[146:147], v[20:21], v[60:61] op_sel_hi:[1,0,1]
	v_pk_fma_f32 v[64:65], v[144:145], v[216:217], v[64:65] op_sel_hi:[1,0,1]
	v_pk_fma_f32 v[58:59], v[146:147], v[216:217], v[58:59] op_sel_hi:[1,0,1]
	s_waitcnt vmcnt(14)
	v_pk_fma_f32 v[62:63], v[148:149], v[20:21], v[62:63] op_sel:[0,1,0] op_sel_hi:[1,1,1]
	v_pk_fma_f32 v[60:61], v[150:151], v[20:21], v[60:61] op_sel:[0,1,0] op_sel_hi:[1,1,1]
	v_pk_fma_f32 v[64:65], v[148:149], v[216:217], v[64:65] op_sel:[0,1,0] op_sel_hi:[1,1,1]
	v_pk_fma_f32 v[58:59], v[150:151], v[216:217], v[58:59] op_sel:[0,1,0] op_sel_hi:[1,1,1]
	s_waitcnt vmcnt(13)
	v_pk_fma_f32 v[62:63], v[152:153], v[22:23], v[62:63] op_sel_hi:[1,0,1]
	v_pk_fma_f32 v[60:61], v[154:155], v[22:23], v[60:61] op_sel_hi:[1,0,1]
	v_pk_fma_f32 v[64:65], v[152:153], v[218:219], v[64:65] op_sel_hi:[1,0,1]
	v_pk_fma_f32 v[58:59], v[154:155], v[218:219], v[58:59] op_sel_hi:[1,0,1]
	s_waitcnt vmcnt(12)
	v_pk_fma_f32 v[62:63], v[156:157], v[22:23], v[62:63] op_sel:[0,1,0] op_sel_hi:[1,1,1]
	v_pk_fma_f32 v[60:61], v[158:159], v[22:23], v[60:61] op_sel:[0,1,0] op_sel_hi:[1,1,1]
	v_pk_fma_f32 v[64:65], v[156:157], v[218:219], v[64:65] op_sel:[0,1,0] op_sel_hi:[1,1,1]
	v_pk_fma_f32 v[58:59], v[158:159], v[218:219], v[58:59] op_sel:[0,1,0] op_sel_hi:[1,1,1]
	s_waitcnt vmcnt(11)
	v_pk_fma_f32 v[62:63], v[164:165], v[24:25], v[62:63] op_sel_hi:[1,0,1]
	v_pk_fma_f32 v[60:61], v[166:167], v[24:25], v[60:61] op_sel_hi:[1,0,1]
	v_pk_fma_f32 v[64:65], v[164:165], v[220:221], v[64:65] op_sel_hi:[1,0,1]
	v_pk_fma_f32 v[58:59], v[166:167], v[220:221], v[58:59] op_sel_hi:[1,0,1]
	s_waitcnt vmcnt(10)
	v_pk_fma_f32 v[62:63], v[168:169], v[24:25], v[62:63] op_sel:[0,1,0] op_sel_hi:[1,1,1]
	v_pk_fma_f32 v[60:61], v[170:171], v[24:25], v[60:61] op_sel:[0,1,0] op_sel_hi:[1,1,1]
	v_pk_fma_f32 v[64:65], v[168:169], v[220:221], v[64:65] op_sel:[0,1,0] op_sel_hi:[1,1,1]
	v_pk_fma_f32 v[58:59], v[170:171], v[220:221], v[58:59] op_sel:[0,1,0] op_sel_hi:[1,1,1]
	s_waitcnt vmcnt(9)
	v_pk_fma_f32 v[62:63], v[172:173], v[26:27], v[62:63] op_sel_hi:[1,0,1]
	v_pk_fma_f32 v[60:61], v[174:175], v[26:27], v[60:61] op_sel_hi:[1,0,1]
	v_pk_fma_f32 v[64:65], v[172:173], v[222:223], v[64:65] op_sel_hi:[1,0,1]
	v_pk_fma_f32 v[58:59], v[174:175], v[222:223], v[58:59] op_sel_hi:[1,0,1]
	s_waitcnt vmcnt(8)
	v_pk_fma_f32 v[62:63], v[176:177], v[26:27], v[62:63] op_sel:[0,1,0] op_sel_hi:[1,1,1]
	v_pk_fma_f32 v[60:61], v[178:179], v[26:27], v[60:61] op_sel:[0,1,0] op_sel_hi:[1,1,1]
	v_pk_fma_f32 v[64:65], v[176:177], v[222:223], v[64:65] op_sel:[0,1,0] op_sel_hi:[1,1,1]
	v_pk_fma_f32 v[58:59], v[178:179], v[222:223], v[58:59] op_sel:[0,1,0] op_sel_hi:[1,1,1]
	s_waitcnt vmcnt(7)
	v_pk_fma_f32 v[62:63], v[180:181], v[28:29], v[62:63] op_sel_hi:[1,0,1]
	v_pk_fma_f32 v[60:61], v[182:183], v[28:29], v[60:61] op_sel_hi:[1,0,1]
	v_pk_fma_f32 v[64:65], v[180:181], v[228:229], v[64:65] op_sel_hi:[1,0,1]
	v_pk_fma_f32 v[58:59], v[182:183], v[228:229], v[58:59] op_sel_hi:[1,0,1]
	s_waitcnt vmcnt(6)
	v_pk_fma_f32 v[62:63], v[184:185], v[28:29], v[62:63] op_sel:[0,1,0] op_sel_hi:[1,1,1]
	v_pk_fma_f32 v[60:61], v[186:187], v[28:29], v[60:61] op_sel:[0,1,0] op_sel_hi:[1,1,1]
	v_pk_fma_f32 v[64:65], v[184:185], v[228:229], v[64:65] op_sel:[0,1,0] op_sel_hi:[1,1,1]
	v_pk_fma_f32 v[58:59], v[186:187], v[228:229], v[58:59] op_sel:[0,1,0] op_sel_hi:[1,1,1]
	s_waitcnt vmcnt(5)
	v_pk_fma_f32 v[62:63], v[188:189], v[30:31], v[62:63] op_sel_hi:[1,0,1]
	v_pk_fma_f32 v[60:61], v[190:191], v[30:31], v[60:61] op_sel_hi:[1,0,1]
	v_pk_fma_f32 v[64:65], v[188:189], v[230:231], v[64:65] op_sel_hi:[1,0,1]
	v_pk_fma_f32 v[58:59], v[190:191], v[230:231], v[58:59] op_sel_hi:[1,0,1]
	s_waitcnt vmcnt(4)
	v_pk_fma_f32 v[62:63], v[192:193], v[30:31], v[62:63] op_sel:[0,1,0] op_sel_hi:[1,1,1]
	v_pk_fma_f32 v[60:61], v[194:195], v[30:31], v[60:61] op_sel:[0,1,0] op_sel_hi:[1,1,1]
	v_pk_fma_f32 v[64:65], v[192:193], v[230:231], v[64:65] op_sel:[0,1,0] op_sel_hi:[1,1,1]
	v_pk_fma_f32 v[58:59], v[194:195], v[230:231], v[58:59] op_sel:[0,1,0] op_sel_hi:[1,1,1]
	s_waitcnt vmcnt(3)
	v_pk_fma_f32 v[62:63], v[196:197], v[32:33], v[62:63] op_sel_hi:[1,0,1]
	v_pk_fma_f32 v[60:61], v[198:199], v[32:33], v[60:61] op_sel_hi:[1,0,1]
	v_pk_fma_f32 v[64:65], v[196:197], v[232:233], v[64:65] op_sel_hi:[1,0,1]
	v_pk_fma_f32 v[58:59], v[198:199], v[232:233], v[58:59] op_sel_hi:[1,0,1]
	s_waitcnt vmcnt(2)
	v_pk_fma_f32 v[62:63], v[200:201], v[32:33], v[62:63] op_sel:[0,1,0] op_sel_hi:[1,1,1]
	v_pk_fma_f32 v[60:61], v[202:203], v[32:33], v[60:61] op_sel:[0,1,0] op_sel_hi:[1,1,1]
	v_pk_fma_f32 v[64:65], v[200:201], v[232:233], v[64:65] op_sel:[0,1,0] op_sel_hi:[1,1,1]
	v_pk_fma_f32 v[58:59], v[202:203], v[232:233], v[58:59] op_sel:[0,1,0] op_sel_hi:[1,1,1]
	s_waitcnt vmcnt(1)
	v_pk_fma_f32 v[62:63], v[204:205], v[34:35], v[62:63] op_sel_hi:[1,0,1]
	v_pk_fma_f32 v[60:61], v[206:207], v[34:35], v[60:61] op_sel_hi:[1,0,1]
	v_pk_fma_f32 v[64:65], v[204:205], v[234:235], v[64:65] op_sel_hi:[1,0,1]
	v_pk_fma_f32 v[58:59], v[206:207], v[234:235], v[58:59] op_sel_hi:[1,0,1]
	s_waitcnt vmcnt(0)
	v_pk_fma_f32 v[62:63], v[208:209], v[34:35], v[62:63] op_sel:[0,1,0] op_sel_hi:[1,1,1]
	v_pk_fma_f32 v[60:61], v[210:211], v[34:35], v[60:61] op_sel:[0,1,0] op_sel_hi:[1,1,1]
	v_pk_fma_f32 v[64:65], v[208:209], v[234:235], v[64:65] op_sel:[0,1,0] op_sel_hi:[1,1,1]
	v_pk_fma_f32 v[58:59], v[210:211], v[234:235], v[58:59] op_sel:[0,1,0] op_sel_hi:[1,1,1]

; __device__ __forceinline__ unsigned pk2(float lo, float hi) { return f2bf(lo) | (f2bf(hi) << 16); }
; #define OPQ(v) asm volatile("" : "+v"(v))
; __device__ __forceinline__ void norm_row(const float* xrow, bf16* orow, const float* g, const float* sh, const float* sc, int lane) {
;     const f32x4* xr = (const f32x4*)xrow + lane;
;     f32x4 v[4]; float s = 0.f;
; #pragma unroll
;     for (int j = 0; j < 4; ++j) { v[j] = xr[64 * j]; s += (v[j].x * v[j].x + v[j].y * v[j].y) + (v[j].z * v[j].z + v[j].w * v[j].w); }
;     const float rs = 1.0f / sqrtf(wave_sum(s) * (1.f / DM) + 1e-6f);
;     unsigned long long* o8 = (unsigned long long*)orow + lane;
; #pragma unroll
;     for (int j = 0; j < 4; ++j) {
;         const f32x4 gg = ((const f32x4*)g)[64 * j + lane], s1 = ((const f32x4*)sc)[64 * j + lane], s0 = ((const f32x4*)sh)[64 * j + lane];
;         const f32x4 h = v[j] * rs * gg * (s1 + 1.0f) + s0;
;         o8[64 * j] = (unsigned long long)pk2(h.x, h.y) | ((unsigned long long)pk2(h.z, h.w) << 32);
;     }
; __global__ void __launch_bounds__(512, 2) hybrid_fwd(Args args) {
;     ...
;     if (IN(1)) { OPQ(lane);
;         for (int m = gw; m < M; m += NGW) { const float* mb = mod + (m >> 13) * NADA; norm_row(x + (size_t)m * DM, XN + (size_t)m * DM, g_ffn1, mb + 0 * DM, mb + 1 * DM, lane); }
.LBB0_121:
	s_cmp_lt_i32 s82, 2
	s_cselect_b64 s[0:1], -1, 0
	s_add_u32 s28, s86, 0x2700000
	s_addc_u32 s29, s87, 0
	s_add_u32 s6, s86, 0xe800000
	s_addc_u32 s7, s87, 0
	s_and_b64 s[12:13], s[0:1], s[12:13]
	s_andn2_b64 vcc, exec, s[12:13]
	s_mov_b32 s96, s91
	s_cbranch_vccnz .LBB0_130
	s_cmpk_gt_i32 s94, 0x3fff
	v_ashrrev_i32_e32 v161, 31, v160
	s_cbranch_scc1 .LBB0_125
	v_mbcnt_lo_u32_b32 v0, -1, 0
	v_mbcnt_hi_u32_b32 v0, -1, v0
	v_and_b32_e32 v1, 64, v0
	v_add_u32_e32 v1, 64, v1
	v_xor_b32_e32 v2, 1, v0
	v_cmp_lt_i32_e32 vcc, v2, v1
	s_mov_b32 s14, s95
	s_ashr_i32 s95, s94, 31
	v_cndmask_b32_e32 v2, v0, v2, vcc
	v_lshlrev_b32_e32 v10, 2, v2
	v_xor_b32_e32 v2, 2, v0
	v_cmp_lt_i32_e32 vcc, v2, v1
	s_lshl_b64 s[0:1], s[94:95], 11
	s_add_u32 s0, s86, s0
	v_cndmask_b32_e32 v2, v0, v2, vcc
	v_lshlrev_b32_e32 v11, 2, v2
	v_xor_b32_e32 v2, 4, v0
	v_cmp_lt_i32_e32 vcc, v2, v1
	s_addc_u32 s1, s87, s1
	s_ashr_i32 s91, s90, 31
	v_cndmask_b32_e32 v2, v0, v2, vcc
	v_lshlrev_b32_e32 v12, 2, v2
	v_xor_b32_e32 v2, 8, v0
	v_cmp_lt_i32_e32 vcc, v2, v1
	s_lshl_b64 s[4:5], s[90:91], 11
	v_mov_b32_e32 v16, 0x358637bd
	v_cndmask_b32_e32 v2, v0, v2, vcc
	v_lshlrev_b32_e32 v13, 2, v2
	v_xor_b32_e32 v2, 16, v0
	v_cmp_lt_i32_e32 vcc, v2, v1
	s_mov_b32 s3, 0xf800000
	v_mov_b32_e32 v17, 0x260
	v_cndmask_b32_e32 v2, v0, v2, vcc
	v_lshlrev_b32_e32 v14, 2, v2
	v_xor_b32_e32 v2, 32, v0
	v_cmp_lt_i32_e32 vcc, v2, v1
	s_mov_b64 s[16:17], 0x1000
	s_movk_i32 s18, 0x1000
	v_cndmask_b32_e32 v0, v0, v2, vcc
	v_lshl_add_u64 v[2:3], v[160:161], 3, s[0:1]
	s_mov_b64 s[0:1], 0x4300600
	v_lshl_add_u64 v[6:7], v[2:3], 0, s[0:1]
	s_lshl_b64 s[0:1], s[94:95], 12
	s_waitcnt lgkmcnt(0)
	s_add_u32 s0, s60, s0
	v_lshlrev_b32_e32 v15, 2, v0
	v_lshlrev_b64 v[0:1], 4, v[160:161]
	s_addc_u32 s1, s61, s1
	v_lshl_add_u64 v[4:5], s[68:69], 0, v[0:1]
	v_lshl_add_u64 v[0:1], s[0:1], 0, v[0:1]
	s_mov_b64 s[0:1], 0x800
	s_mov_b32 s95, s14
	v_lshl_add_u64 v[8:9], v[0:1], 0, s[0:1]
	s_lshl_b64 s[14:15], s[90:91], 12
	s_movk_i32 s19, 0x7fff
	s_mov_b32 s20, 0xffff0000
	s_mov_b32 s21, s94
	s_mov_b32 s98, -1
	global_load_dwordx4 v[64:67], v[4:5], off
	global_load_dwordx4 v[68:71], v[4:5], off offset:1024
	global_load_dwordx4 v[72:75], v[4:5], off offset:2048
	global_load_dwordx4 v[76:79], v[4:5], off offset:3072
	global_load_dwordx4 v[112:115], v[8:9], off offset:-2048
	global_load_dwordx4 v[116:119], v[8:9], off offset:-1024
	global_load_dwordx4 v[120:123], v[8:9], off
	global_load_dwordx4 v[124:127], v[8:9], off offset:1024
.LBB0_124:
	s_ashr_i32 s0, s21, 13
	s_cmp_eq_u32 s0, s98
	s_cbranch_scc1 .Lnorm_same
	s_mov_b32 s98, s0
	s_mulk_i32 s0, 0x2400
	s_ashr_i32 s1, s0, 31
	s_lshl_b64 s[0:1], s[0:1], 2
	s_add_u32 s0, s22, s0
	s_addc_u32 s1, s23, s1
	v_lshl_add_u64 v[42:43], v[160:161], 4, s[0:1]
	v_lshl_add_u64 v[44:45], v[42:43], 0, s[16:17]
	global_load_dwordx4 v[96:99], v[42:43], off
	global_load_dwordx4 v[100:103], v[42:43], off offset:1024
	global_load_dwordx4 v[104:107], v[42:43], off offset:2048
	global_load_dwordx4 v[108:111], v[42:43], off offset:3072
	global_load_dwordx4 v[80:83], v[44:45], off
	global_load_dwordx4 v[84:87], v[44:45], off offset:1024
	global_load_dwordx4 v[88:91], v[44:45], off offset:2048
	global_load_dwordx4 v[92:95], v[44:45], off offset:3072
	s_waitcnt vmcnt(0)
	v_pk_add_f32 v[80:81], v[80:81], 1.0 op_sel_hi:[1,0]
	v_pk_add_f32 v[82:83], v[82:83], 1.0 op_sel_hi:[1,0]
	v_pk_add_f32 v[84:85], v[84:85], 1.0 op_sel_hi:[1,0]
	v_pk_add_f32 v[86:87], v[86:87], 1.0 op_sel_hi:[1,0]
	v_pk_add_f32 v[88:89], v[88:89], 1.0 op_sel_hi:[1,0]
	v_pk_add_f32 v[90:91], v[90:91], 1.0 op_sel_hi:[1,0]
	v_pk_add_f32 v[92:93], v[92:93], 1.0 op_sel_hi:[1,0]
	v_pk_add_f32 v[94:95], v[94:95], 1.0 op_sel_hi:[1,0]
.Lnorm_same:
	s_waitcnt vmcnt(4)
	v_mov_b32_e32 v18, v112
	v_mov_b32_e32 v19, v113
	v_mov_b32_e32 v20, v114
	v_mov_b32_e32 v21, v115
	v_mov_b32_e32 v22, v116
	v_mov_b32_e32 v23, v117
	v_mov_b32_e32 v24, v118
	v_mov_b32_e32 v25, v119
	v_mov_b32_e32 v26, v120
	v_mov_b32_e32 v27, v121
	v_mov_b32_e32 v28, v122
	v_mov_b32_e32 v29, v123
	v_mov_b32_e32 v0, v124
	v_mov_b32_e32 v1, v125
	v_mov_b32_e32 v2, v126
	v_mov_b32_e32 v3, v127
	s_add_i32 s21, s21, s90
	v_lshl_add_u64 v[8:9], v[8:9], 0, s[14:15]
	s_cmpk_gt_i32 s21, 0x3fff
	s_cbranch_scc1 .Lnorm_nopf
	global_load_dwordx4 v[112:115], v[8:9], off offset:-2048
	global_load_dwordx4 v[116:119], v[8:9], off offset:-1024
	global_load_dwordx4 v[120:123], v[8:9], off
	global_load_dwordx4 v[124:127], v[8:9], off offset:1024
; __device__ __forceinline__ unsigned pk2(float lo, float hi) { return f2bf(lo) | (f2bf(hi) << 16); }
; __device__ __forceinline__ void norm_row(const float* xrow, bf16* orow, const float* g, const float* sh, const float* sc, int lane) {
;     const f32x4* xr = (const f32x4*)xrow + lane;
;     f32x4 v[4]; float s = 0.f;
; #pragma unroll
;     for (int j = 0; j < 4; ++j) { v[j] = xr[64 * j]; s += (v[j].x * v[j].x + v[j].y * v[j].y) + (v[j].z * v[j].z + v[j].w * v[j].w); }
;     const float rs = 1.0f / sqrtf(wave_sum(s) * (1.f / DM) + 1e-6f);
;     unsigned long long* o8 = (unsigned long long*)orow + lane;
; #pragma unroll
;     for (int j = 0; j < 4; ++j) {
;         const f32x4 gg = ((const f32x4*)g)[64 * j + lane], s1 = ((const f32x4*)sc)[64 * j + lane], s0 = ((const f32x4*)sh)[64 * j + lane];
;         const f32x4 h = v[j] * rs * gg * (s1 + 1.0f) + s0;
;         o8[64 * j] = (unsigned long long)pk2(h.x, h.y) | ((unsigned long long)pk2(h.z, h.w) << 32);
;     }
.Lnorm_nopf:
	v_pk_mul_f32 v[46:47], v[20:21], v[20:21]
	v_pk_mul_f32 v[48:49], v[18:19], v[18:19]
	v_pk_mul_f32 v[50:51], v[24:25], v[24:25]
	v_pk_mul_f32 v[52:53], v[22:23], v[22:23]
	v_pk_mov_b32 v[58:59], v[48:49], v[46:47] op_sel:[1,0]
	v_mov_b32_e32 v49, v47
	v_pk_mov_b32 v[46:47], v[52:53], v[50:51] op_sel:[1,0]
	v_mov_b32_e32 v53, v51
	v_mul_f32_e32 v57, v0, v0
	v_mul_f32_e32 v54, v27, v27
	v_mul_f32_e32 v56, v29, v29
	v_pk_add_f32 v[48:49], v[58:59], v[48:49]
	v_pk_add_f32 v[46:47], v[46:47], v[52:53]
	v_mul_f32_e32 v60, v1, v1
	v_mul_f32_e32 v61, v2, v2
	v_mul_f32_e32 v62, v3, v3
	v_pk_fma_f32 v[50:51], v[26:27], v[26:27], v[54:55] op_sel_hi:[1,1,0]
	v_pk_fma_f32 v[54:55], v[28:29], v[28:29], v[56:57] op_sel_hi:[1,1,0]
	v_pk_add_f32 v[48:49], v[48:49], v[48:49] op_sel:[0,1] op_sel_hi:[1,0]
	v_pk_add_f32 v[46:47], v[46:47], v[46:47] op_sel:[0,1] op_sel_hi:[1,0]
	v_mov_b32_e32 v51, v61
	v_mov_b32_e32 v55, v62
	v_mov_b32_e32 v49, v57
	v_mov_b32_e32 v47, v60
	v_pk_add_f32 v[50:51], v[50:51], v[54:55]
	v_pk_add_f32 v[46:47], v[48:49], v[46:47]
	v_pk_add_f32 v[46:47], v[46:47], v[50:51]
	v_add_f32_e32 v46, v46, v47
	ds_bpermute_b32 v47, v10, v46
	s_waitcnt lgkmcnt(0)
	v_add_f32_e32 v46, v46, v47
	ds_bpermute_b32 v47, v11, v46
	s_waitcnt lgkmcnt(0)
	v_add_f32_e32 v46, v46, v47
	ds_bpermute_b32 v47, v12, v46
	s_waitcnt lgkmcnt(0)
	v_add_f32_e32 v46, v46, v47
	ds_bpermute_b32 v47, v13, v46
	s_waitcnt lgkmcnt(0)
	v_add_f32_e32 v46, v46, v47
	ds_bpermute_b32 v47, v14, v46
	s_waitcnt lgkmcnt(0)
	v_add_f32_e32 v46, v46, v47
	ds_bpermute_b32 v47, v15, v46
	s_waitcnt lgkmcnt(0)
	v_add_f32_e32 v46, v46, v47
	v_fmamk_f32 v46, v46, 0x3a800000, v16
	v_mul_f32_e32 v47, 0x4f800000, v46
	v_cmp_gt_f32_e32 vcc, s3, v46
	s_nop 1
	v_cndmask_b32_e32 v46, v46, v47, vcc
	v_sqrt_f32_e32 v47, v46
	s_nop 0
	v_add_u32_e32 v48, -1, v47
	v_add_u32_e32 v49, 1, v47
	v_fma_f32 v50, -v48, v47, v46
	v_fma_f32 v51, -v49, v47, v46
	v_cmp_ge_f32_e64 s[0:1], 0, v50
	s_nop 1
	v_cndmask_b32_e64 v47, v47, v48, s[0:1]
	v_cmp_lt_f32_e64 s[0:1], 0, v51
	s_nop 1
	v_cndmask_b32_e64 v47, v47, v49, s[0:1]
	v_mul_f32_e32 v48, 0x37800000, v47
	v_cndmask_b32_e32 v47, v47, v48, vcc
	v_cmp_class_f32_e32 vcc, v46, v17
	s_nop 1
	v_cndmask_b32_e32 v46, v47, v46, vcc
	v_div_scale_f32 v47, s[0:1], v46, v46, 1.0
	v_rcp_f32_e32 v49, v47
	v_div_scale_f32 v48, vcc, 1.0, v46, 1.0
	v_fma_f32 v50, -v47, v49, 1.0
	v_fmac_f32_e32 v49, v50, v49
	v_mul_f32_e32 v50, v48, v49
	v_fma_f32 v51, -v47, v50, v48
	v_fmac_f32_e32 v50, v51, v49
	v_fma_f32 v47, -v47, v50, v48
	v_div_fmas_f32 v47, v47, v49, v50
	v_div_fixup_f32 v46, v47, v46, 1.0
	v_pk_mul_f32 v[20:21], v[20:21], v[46:47] op_sel_hi:[1,0]
	v_pk_mul_f32 v[18:19], v[18:19], v[46:47] op_sel_hi:[1,0]
	v_pk_mul_f32 v[20:21], v[66:67], v[20:21]
	v_pk_mul_f32 v[18:19], v[64:65], v[18:19]
	v_pk_fma_f32 v[20:21], v[82:83], v[20:21], v[98:99]
	v_pk_fma_f32 v[18:19], v[80:81], v[18:19], v[96:97]
	v_bfe_u32 v32, v20, 16, 1
	v_bfe_u32 v30, v18, 16, 1
	v_bfe_u32 v31, v19, 16, 1
	v_bfe_u32 v33, v21, 16, 1
	v_add3_u32 v18, v18, v30, s19
	v_add3_u32 v20, v20, v32, s19
	v_add3_u32 v19, v19, v31, s19
	v_add3_u32 v21, v21, v33, s19
	v_lshrrev_b32_e32 v18, 16, v18
	v_lshrrev_b32_e32 v20, 16, v20
	v_and_or_b32 v34, v19, s20, v18
	v_and_or_b32 v35, v21, s20, v20
	global_store_dwordx2 v[6:7], v[34:35], off offset:-1536
	v_pk_mul_f32 v[24:25], v[24:25], v[46:47] op_sel_hi:[1,0]
	v_pk_mul_f32 v[22:23], v[22:23], v[46:47] op_sel_hi:[1,0]
	v_pk_mul_f32 v[24:25], v[70:71], v[24:25]
	v_pk_mul_f32 v[22:23], v[68:69], v[22:23]
	v_pk_fma_f32 v[24:25], v[86:87], v[24:25], v[102:103]
	v_pk_fma_f32 v[22:23], v[84:85], v[22:23], v[100:101]
	v_bfe_u32 v32, v24, 16, 1
	v_bfe_u32 v30, v22, 16, 1
	v_bfe_u32 v31, v23, 16, 1
	v_bfe_u32 v33, v25, 16, 1
	v_add3_u32 v22, v22, v30, s19
	v_add3_u32 v24, v24, v32, s19
	v_add3_u32 v23, v23, v31, s19
	v_add3_u32 v25, v25, v33, s19
	v_lshrrev_b32_e32 v22, 16, v22
	v_lshrrev_b32_e32 v24, 16, v24
	v_and_or_b32 v36, v23, s20, v22
	v_and_or_b32 v37, v25, s20, v24
	global_store_dwordx2 v[6:7], v[36:37], off offset:-1024
	v_pk_mul_f32 v[28:29], v[28:29], v[46:47] op_sel_hi:[1,0]
	v_pk_mul_f32 v[26:27], v[26:27], v[46:47] op_sel_hi:[1,0]
	v_pk_mul_f32 v[28:29], v[74:75], v[28:29]
	v_pk_mul_f32 v[26:27], v[72:73], v[26:27]
	v_pk_fma_f32 v[28:29], v[90:91], v[28:29], v[106:107]
	v_pk_fma_f32 v[26:27], v[88:89], v[26:27], v[104:105]
	v_bfe_u32 v32, v28, 16, 1
	v_bfe_u32 v30, v26, 16, 1
	v_bfe_u32 v31, v27, 16, 1
	v_bfe_u32 v33, v29, 16, 1
	v_add3_u32 v26, v26, v30, s19
	v_add3_u32 v28, v28, v32, s19
	v_add3_u32 v27, v27, v31, s19
	v_add3_u32 v29, v29, v33, s19
	v_lshrrev_b32_e32 v26, 16, v26
	v_lshrrev_b32_e32 v28, 16, v28
	v_and_or_b32 v38, v27, s20, v26
	v_and_or_b32 v39, v29, s20, v28
	global_store_dwordx2 v[6:7], v[38:39], off offset:-512
	v_pk_mul_f32 v[2:3], v[2:3], v[46:47] op_sel_hi:[1,0]
	v_pk_mul_f32 v[0:1], v[0:1], v[46:47] op_sel_hi:[1,0]
	v_pk_mul_f32 v[2:3], v[78:79], v[2:3]
	v_pk_mul_f32 v[0:1], v[76:77], v[0:1]
	v_pk_fma_f32 v[2:3], v[94:95], v[2:3], v[110:111]
	v_pk_fma_f32 v[0:1], v[92:93], v[0:1], v[108:109]
	v_bfe_u32 v32, v2, 16, 1
	v_bfe_u32 v30, v0, 16, 1
	v_bfe_u32 v31, v1, 16, 1
	v_bfe_u32 v33, v3, 16, 1
	v_add3_u32 v0, v0, v30, s19
	v_add3_u32 v2, v2, v32, s19
	v_add3_u32 v1, v1, v31, s19
	v_add3_u32 v3, v3, v33, s19
	v_lshrrev_b32_e32 v0, 16, v0
	v_lshrrev_b32_e32 v2, 16, v2
	v_and_or_b32 v40, v1, s20, v0
	v_and_or_b32 v41, v3, s20, v2
	global_store_dwordx2 v[6:7], v[40:41], off
	v_lshl_add_u64 v[6:7], v[6:7], 0, s[4:5]
	s_cmpk_gt_i32 s21, 0x3fff
	s_cbranch_scc0 .LBB0_124

;     __device__ bool next(int i, Unit& u) const { if (i > 1 || !so.next(0, u)) return false; if (i == 1) { u.pm += 64; u.pn += 4; } return true; }
; #define LAS __attribute__((address_space(3)))
; __global__ void __launch_bounds__(512, 2) hybrid_fwd(Args args) {
;     ...
;     if (IN(4)) { pg8::StaticOrder S; S.init(M, NIN, G, blk); pg8::Unit u0; u0.pm = 0; u0.pn = 0; S.next(0, u0); const int bb = u0.pm >> 5;
;         LAS float* rsl = (LAS float*)(lds + 131072 + 1024);
;         LAS float* bl = (LAS float*)(lds + 131072 + 2048); LAS float* qkg = (LAS float*)(lds + 131072 + 8192);
;         if (tid < 256) { rsl[tid] = pg8::rstd_row(ROWP2, u0.pm * 256 + tid); pg8::Unit uu; for (int i = 0; S.next(i, uu); ++i) bl[i * 256 + tid] = BIAS[(size_t)bb * NBIAS + uu.pn * 256 + tid]; }
;         else if (tid < 384) qkg[tid - 256] = tid < 320 ? q_gain[tid - 256] : k_gain[tid - 320];
.LBB0_377:
	s_or_saveexec_b64 s[6:7], s[0:1]
	s_ashr_i32 s12, s13, 5
	s_xor_b64 exec, exec, s[6:7]
	s_cbranch_execz .LBB0_388
	v_lshl_or_b32 v0, s13, 8, v226
	s_waitcnt lgkmcnt(0)
	v_ashrrev_i32_e32 v1, 31, v0
	v_lshlrev_b64 v[0:1], 6, v[0:1]
	v_lshl_add_u64 v[0:1], s[8:9], 0, v[0:1]
	global_load_dwordx4 v[4:7], v[0:1], off
	global_load_dwordx4 v[8:11], v[0:1], off offset:32
	global_load_dwordx4 v[12:15], v[0:1], off offset:16
	global_load_dwordx4 v[16:19], v[0:1], off offset:48
	s_mul_i32 s14, s12, 0x9800
	s_lshr_b32 s15, s2, 6
	s_lshl_b32 s15, s15, 10
	s_add_i32 s14, s14, s15
	s_add_u32 s14, s67, s14
	s_addc_u32 s15, s66, 0
	v_lshlrev_b32_e32 v27, 2, v226
	global_load_dword v28, v27, s[14:15]
	s_add_u32 s14, s14, 0x1000
	s_addc_u32 s15, s15, 0
	global_load_dword v29, v27, s[14:15]
	s_add_u32 s14, s14, 0x1000
	s_addc_u32 s15, s15, 0
	global_load_dword v30, v27, s[14:15]
	s_add_u32 s14, s14, 0x1000
	s_addc_u32 s15, s15, 0
	global_load_dword v31, v27, s[14:15]
	v_mov_b32_e32 v24, 0x358637bd
	s_mov_b32 s0, 0xf800000
	s_ashr_i32 s13, s42, 31
	s_mul_i32 s8, s12, 0x9800
	s_mul_hi_i32 s1, s12, 0x9800
	s_add_u32 s8, s67, s8
	s_addc_u32 s9, s66, s1
	v_mov_b32_e32 v25, 0x260
	v_lshlrev_b32_e32 v20, 2, v226
	v_mov_b32_e32 v21, 0
	v_add_u32_e32 v26, 0, v20
	s_mov_b32 s16, s42
	v_mov_b64_e32 v[0:1], 0x400
	v_mov_b64_e32 v[2:3], 0x3ff
	s_waitcnt vmcnt(0)
	v_mov_b32_e32 v22, v4
	v_mov_b32_e32 v23, v8
	v_mov_b32_e32 v8, v5
	v_mov_b32_e32 v4, v6
	v_mov_b32_e32 v5, v10
	v_mov_b32_e32 v10, v7
	v_mov_b32_e32 v6, v12
	v_mov_b32_e32 v7, v16
	v_mov_b32_e32 v16, v13
	v_mov_b32_e32 v12, v14
	v_mov_b32_e32 v13, v18
	v_mov_b32_e32 v18, v15
	v_pk_add_f32 v[8:9], v[22:23], v[8:9]
	v_pk_add_f32 v[4:5], v[4:5], v[10:11]
	v_pk_add_f32 v[6:7], v[6:7], v[16:17]
	v_pk_add_f32 v[10:11], v[12:13], v[18:19]
	v_pk_add_f32 v[4:5], v[8:9], v[4:5]
	v_pk_add_f32 v[6:7], v[6:7], v[10:11]
	s_nop 0
	v_pk_add_f32 v[4:5], v[4:5], v[6:7]
	v_add_u32_e32 v7, 0x20400, v26
	v_add_f32_e32 v4, v4, v5
	v_fmac_f32_e32 v24, 0x3a800000, v4
	v_mul_f32_e32 v4, 0x4f800000, v24
	v_cmp_gt_f32_e32 vcc, s0, v24
	v_add_u32_e32 v6, 0x20800, v26
	s_nop 0
	v_cndmask_b32_e32 v4, v24, v4, vcc
	v_sqrt_f32_e32 v5, v4
	s_nop 0
	v_add_u32_e32 v8, -1, v5
	v_add_u32_e32 v9, 1, v5
	v_fma_f32 v10, -v8, v5, v4
	v_fma_f32 v11, -v9, v5, v4
	v_cmp_ge_f32_e64 s[0:1], 0, v10
	s_nop 1
	v_cndmask_b32_e64 v5, v5, v8, s[0:1]
	v_cmp_lt_f32_e64 s[0:1], 0, v11
	s_nop 1
	v_cndmask_b32_e64 v5, v5, v9, s[0:1]
	v_mul_f32_e32 v8, 0x37800000, v5
	v_cndmask_b32_e32 v5, v5, v8, vcc
	v_cmp_class_f32_e32 vcc, v4, v25
	s_nop 1
	v_cndmask_b32_e32 v8, v5, v4, vcc
	v_div_scale_f32 v9, s[0:1], v8, v8, 1.0
	v_rcp_f32_e32 v10, v9
	v_div_scale_f32 v11, vcc, 1.0, v8, 1.0
	v_lshl_add_u64 v[4:5], s[8:9], 0, v[20:21]
	v_fma_f32 v12, -v9, v10, 1.0
	v_fmac_f32_e32 v10, v12, v10
	v_mul_f32_e32 v12, v11, v10
	v_fma_f32 v13, -v9, v12, v11
	v_fmac_f32_e32 v12, v13, v10
	v_fma_f32 v9, -v9, v12, v11
	v_div_fmas_f32 v9, v9, v10, v12
	v_div_fixup_f32 v8, v9, v8, 1.0
	s_mov_b64 s[8:9], s[2:3]
	ds_write_b32 v7, v8
	ds_write_b32 v6, v28
	ds_write_b32 v6, v29 offset:1024
	ds_write_b32 v6, v30 offset:2048
	ds_write_b32 v6, v31 offset:3072

;     __device__ bool next(int i, Unit& u) const { if (i > 1 || !so.next(0, u)) return false; if (i == 1) { u.pm += 64; u.pn += 4; } return true; }
; #define LAS __attribute__((address_space(3)))
; __global__ void __launch_bounds__(512, 2) hybrid_fwd(Args args) {
;     ...
;     if (IN(8)) { pg8::StaticOrder S; S.init(M, NFF, G, blk); pg8::Unit u0; u0.pm = 0; u0.pn = 0; S.next(0, u0); const int bb = u0.pm >> 5;
;         LAS float* rsl = (LAS float*)(lds + 131072 + 1024);
;         LAS float* bl = (LAS float*)(lds + 131072 + 2048);
;         if (tid < 256) { rsl[tid] = pg8::rstd_row(ROWP3, u0.pm * 256 + tid); pg8::Unit uu; for (int i = 0; S.next(i, uu); ++i) bl[i * 256 + tid] = BIAS[(size_t)bb * NBIAS + NIN + uu.pn * 256 + tid]; }
;         __syncthreads();
.LBB0_888:
	s_ashr_i32 s10, s14, 5
	s_movk_i32 s11, 0xff
	s_ashr_i32 s3, s2, 31
	v_cmp_lt_i32_e32 vcc, s11, v162
	s_and_saveexec_b64 s[12:13], vcc
	s_xor_b64 s[12:13], exec, s[12:13]
	s_ashr_i32 s11, s10, 31
	s_or_saveexec_b64 s[12:13], s[12:13]
	s_waitcnt lgkmcnt(0)
	v_mov_b64_e32 v[0:1], s[10:11]
	s_xor_b64 exec, exec, s[12:13]
	s_cbranch_execz .LBB0_898
	v_lshl_add_u32 v0, s14, 8, v162
	v_ashrrev_i32_e32 v1, 31, v0
	v_lshlrev_b64 v[0:1], 6, v[0:1]
	v_lshl_add_u64 v[0:1], s[0:1], 0, v[0:1]
	global_load_dwordx4 v[4:7], v[0:1], off
	global_load_dwordx4 v[8:11], v[0:1], off offset:32
	global_load_dwordx4 v[12:15], v[0:1], off offset:16
	global_load_dwordx4 v[16:19], v[0:1], off offset:48
	s_mul_i32 s20, s10, 0x9800
	s_lshr_b32 s21, s2, 6
	s_lshl_b32 s21, s21, 10
	s_add_i32 s20, s20, s21
	s_add_i32 s20, s20, 0x4000
	s_add_u32 s20, s67, s20
	s_addc_u32 s21, s66, 0
	v_lshlrev_b32_e32 v26, 2, v162
	global_load_dword v27, v26, s[20:21]
	s_add_u32 s20, s20, 0x1000
	s_addc_u32 s21, s21, 0
	global_load_dword v28, v26, s[20:21]
	s_add_u32 s20, s20, 0x1000
	s_addc_u32 s21, s21, 0
	global_load_dword v29, v26, s[20:21]
	s_add_u32 s20, s20, 0x1000
	s_addc_u32 s21, s21, 0
	global_load_dword v30, v26, s[20:21]
	s_add_u32 s20, s20, 0x1000
	s_addc_u32 s21, s21, 0
	global_load_dword v31, v26, s[20:21]
	s_add_u32 s20, s20, 0x1000
	s_addc_u32 s21, s21, 0
	global_load_dword v32, v26, s[20:21]
	v_mov_b32_e32 v22, 0x358637bd
	s_mov_b32 s1, 0xf800000
	s_ashr_i32 s16, s42, 31
	s_ashr_i32 s11, s10, 31
	s_mul_i32 s0, s10, 0x9800
	s_mul_hi_i32 s19, s10, 0x9800
	s_add_u32 s0, s67, s0
	v_ashrrev_i32_e32 v163, 31, v162
	v_mov_b32_e32 v23, 0x260
	v_lshl_add_u32 v24, v162, 2, 0
	s_mov_b64 s[14:15], 0x4000
	s_mov_b32 s17, s42
	s_movk_i32 s18, 0xb1
	v_mov_b64_e32 v[0:1], 0x580
	v_mov_b64_e32 v[2:3], 0x57f
	v_add_u32_e32 v25, 0x20400, v24
	s_waitcnt vmcnt(0)
	v_mov_b32_e32 v20, v4
	v_mov_b32_e32 v21, v8
	v_mov_b32_e32 v8, v5
	v_mov_b32_e32 v4, v6
	v_mov_b32_e32 v5, v10
	v_mov_b32_e32 v10, v7
	v_mov_b32_e32 v6, v12
	v_mov_b32_e32 v7, v16
	v_mov_b32_e32 v16, v13
	v_mov_b32_e32 v12, v14
	v_mov_b32_e32 v13, v18
	v_mov_b32_e32 v18, v15
	v_pk_add_f32 v[8:9], v[20:21], v[8:9]
	v_pk_add_f32 v[4:5], v[4:5], v[10:11]
	v_pk_add_f32 v[6:7], v[6:7], v[16:17]
	v_pk_add_f32 v[10:11], v[12:13], v[18:19]
	v_pk_add_f32 v[4:5], v[8:9], v[4:5]
	v_pk_add_f32 v[6:7], v[6:7], v[10:11]
	s_nop 0
	v_pk_add_f32 v[4:5], v[4:5], v[6:7]
	v_add_u32_e32 v6, 0x20800, v24
	v_add_f32_e32 v4, v4, v5
	v_fmac_f32_e32 v22, 0x3a800000, v4
	v_mul_f32_e32 v4, 0x4f800000, v22
	v_cmp_gt_f32_e32 vcc, s1, v22
	s_addc_u32 s1, s66, s19
	s_nop 0
	v_cndmask_b32_e32 v7, v22, v4, vcc
	v_sqrt_f32_e32 v8, v7
	v_lshl_add_u64 v[4:5], v[162:163], 2, s[0:1]
	v_lshl_add_u64 v[4:5], v[4:5], 0, s[14:15]
	s_mov_b64 s[14:15], s[2:3]
	v_add_u32_e32 v9, -1, v8
	v_add_u32_e32 v10, 1, v8
	v_fma_f32 v11, -v9, v8, v7
	v_fma_f32 v12, -v10, v8, v7
	v_cmp_ge_f32_e64 s[0:1], 0, v11
	s_nop 1
	v_cndmask_b32_e64 v8, v8, v9, s[0:1]
	v_cmp_lt_f32_e64 s[0:1], 0, v12
	s_nop 1
	v_cndmask_b32_e64 v8, v8, v10, s[0:1]
	v_mul_f32_e32 v9, 0x37800000, v8
	v_cndmask_b32_e32 v8, v8, v9, vcc
	v_cmp_class_f32_e32 vcc, v7, v23
	s_nop 1
	v_cndmask_b32_e32 v7, v8, v7, vcc
	v_div_scale_f32 v8, s[0:1], v7, v7, 1.0
	v_rcp_f32_e32 v9, v8
	v_div_scale_f32 v10, vcc, 1.0, v7, 1.0
	v_fma_f32 v11, -v8, v9, 1.0
	v_fmac_f32_e32 v9, v11, v9
	v_mul_f32_e32 v11, v10, v9
	v_fma_f32 v12, -v8, v11, v10
	v_fmac_f32_e32 v11, v12, v9
	v_fma_f32 v8, -v8, v11, v10
	v_div_fmas_f32 v8, v8, v9, v11
	v_div_fixup_f32 v7, v8, v7, 1.0
	ds_write_b32 v25, v7
	ds_write_b32 v6, v27
	ds_write_b32 v6, v28 offset:1024
	ds_write_b32 v6, v29 offset:2048
	ds_write_b32 v6, v30 offset:3072
	ds_write_b32 v6, v31 offset:4096
	ds_write_b32 v6, v32 offset:5120

; __global__ void __launch_bounds__(512, 2) hybrid_fwd(Args args) {
	.amdhsa_kernel _Z10hybrid_fwd4Args
		.amdhsa_group_segment_fixed_size 0
		.amdhsa_private_segment_fixed_size 0
		.amdhsa_kernarg_size 440
		.amdhsa_user_sgpr_count 2
		.amdhsa_user_sgpr_dispatch_ptr 0
		.amdhsa_user_sgpr_queue_ptr 0
		.amdhsa_user_sgpr_kernarg_segment_ptr 1
		.amdhsa_user_sgpr_dispatch_id 0
		.amdhsa_user_sgpr_kernarg_preload_length 0
		.amdhsa_user_sgpr_kernarg_preload_offset 0
		.amdhsa_user_sgpr_private_segment_size 0
		.amdhsa_uses_dynamic_stack 0
		.amdhsa_enable_private_segment 0
		.amdhsa_system_sgpr_workgroup_id_x 1
		.amdhsa_system_sgpr_workgroup_id_y 0
		.amdhsa_system_sgpr_workgroup_id_z 0
		.amdhsa_system_sgpr_workgroup_info 0
		.amdhsa_system_vgpr_workitem_id 2
		.amdhsa_next_free_vgpr 253
		.amdhsa_next_free_sgpr 102
		.amdhsa_accum_offset 256
		.amdhsa_reserve_vcc 1
		.amdhsa_float_round_mode_32 0
		.amdhsa_float_round_mode_16_64 0
		.amdhsa_float_denorm_mode_32 3
		.amdhsa_float_denorm_mode_16_64 3
		.amdhsa_dx10_clamp 1
		.amdhsa_ieee_mode 1
		.amdhsa_fp16_overflow 0
		.amdhsa_tg_split 0
		.amdhsa_exception_fp_ieee_invalid_op 0
		.amdhsa_exception_fp_denorm_src 0
		.amdhsa_exception_fp_ieee_div_zero 0
		.amdhsa_exception_fp_ieee_overflow 0
		.amdhsa_exception_fp_ieee_underflow 0
		.amdhsa_exception_fp_ieee_inexact 0
		.amdhsa_exception_int_div_zero 0
	.end_amdhsa_kernel

; __global__ void __launch_bounds__(512, 2) hybrid_fwd(Args args) {
amdhsa.kernels:
  - .agpr_count:     0
    .args:
      - .offset:         0
        .size:           184
        .value_kind:     by_value
      - .offset:         184
        .size:           4
        .value_kind:     hidden_block_count_x
      - .offset:         188
        .size:           4
        .value_kind:     hidden_block_count_y
      - .offset:         192
        .size:           4
        .value_kind:     hidden_block_count_z
      - .offset:         196
        .size:           2
        .value_kind:     hidden_group_size_x
      - .offset:         198
        .size:           2
        .value_kind:     hidden_group_size_y
      - .offset:         200
        .size:           2
        .value_kind:     hidden_group_size_z
      - .offset:         202
        .size:           2
        .value_kind:     hidden_remainder_x
      - .offset:         204
        .size:           2
        .value_kind:     hidden_remainder_y
      - .offset:         206
        .size:           2
        .value_kind:     hidden_remainder_z
      - .offset:         224
        .size:           8
        .value_kind:     hidden_global_offset_x
      - .offset:         232
        .size:           8
        .value_kind:     hidden_global_offset_y
      - .offset:         240
        .size:           8
        .value_kind:     hidden_global_offset_z
      - .offset:         248
        .size:           2
        .value_kind:     hidden_grid_dims
      - .offset:         272
        .size:           8
        .value_kind:     hidden_multigrid_sync_arg
      - .offset:         304
        .size:           4
        .value_kind:     hidden_dynamic_lds_size
    .group_segment_fixed_size: 0
    .kernarg_segment_align: 8
    .kernarg_segment_size: 440
    .language:       OpenCL C
    .language_version:
      - 2
      - 0
    .max_flat_workgroup_size: 512
    .name:           _Z10hybrid_fwd4Args
    .private_segment_fixed_size: 0
    .sgpr_count:     108
    .sgpr_spill_count: 13
    .symbol:         _Z10hybrid_fwd4Args.kd
    .uniform_work_group_size: 1
    .uses_dynamic_stack: false
    .vgpr_count:     253
    .vgpr_spill_count: 0
    .wavefront_size: 64
